# up-GEMM conv epilogue: rstd-table row partial-sum chain keeps 4 chunk loads in flight instead of one load per wait
# speedup vs baseline: 1.0171x; 1.0171x over previous
; __device__ __forceinline__ float rstd_of(float ssq) { return __builtin_amdgcn_rsqf(ssq * (1.0f / DM) + RMS_EPS); }
; __device__ __forceinline__ float row_ssq(const float* part, int row, int np4) { const f32x4* p = (const f32x4*)(part + (size_t)row * 64); f32x4 a = p[0];
; #pragma unroll 8
;     for (int j = 1; j < np4; ++j) a += p[j];
;     return (a[0] + a[1]) + (a[2] + a[3]); }
;     __device__ __forceinline__ void operator()(const f32x4 (&acc)[2][2][4][2], const Unit& u, int wr, int wc, int fr, int fq) const {
;     ...
;         if (!u.same_pm) { const int t = (wr * 4 + wc) * 64 + fq * 16 + fr;
;           if (t < 256) ct[t] = rstd_of(row_ssq(rsq, u.pm * BM + t, np4));
;           asm volatile("s_waitcnt lgkmcnt(0)\n\ts_barrier" ::: "memory"); }
.LBB0_1086:
	s_andn2_b64 vcc, exec, s[54:55]
	s_cbranch_vccnz .LBB0_1096
	s_and_saveexec_b64 s[14:15], s[6:7]
	s_cbranch_execz .LBB0_1095
	v_lshl_add_u32 v106, s60, 8, v248
	v_ashrrev_i32_e32 v107, 31, v106
	v_readlane_b32 s34, v255, 31
	v_lshlrev_b64 v[126:127], 8, v[106:107]
	v_readlane_b32 s35, v255, 32
	s_mov_b32 s3, 1
	s_nop 0
	v_lshl_add_u64 v[106:107], s[34:35], 0, v[126:127]
	v_mov_b32_e32 v240, v106
	v_mov_b32_e32 v241, v107
	v_readlane_b32 s34, v255, 29
	v_readlane_b32 s35, v255, 30
	global_load_dwordx4 v[106:109], v[240:241], off
	global_load_dwordx4 v[224:227], v[240:241], off offset:16
	global_load_dwordx4 v[228:231], v[240:241], off offset:32
	global_load_dwordx4 v[232:235], v[240:241], off offset:48
	global_load_dwordx4 v[236:239], v[240:241], off offset:64
	s_andn2_b64 vcc, exec, s[34:35]
	s_cbranch_vccnz .Lepc_np8
	s_waitcnt vmcnt(3)
	v_pk_add_f32 v[108:109], v[108:109], v[226:227]
	v_pk_add_f32 v[106:107], v[106:107], v[224:225]
	global_load_dwordx4 v[224:227], v[240:241], off offset:80
	s_waitcnt vmcnt(3)
	v_pk_add_f32 v[108:109], v[108:109], v[230:231]
	v_pk_add_f32 v[106:107], v[106:107], v[228:229]
	global_load_dwordx4 v[228:231], v[240:241], off offset:96
	s_waitcnt vmcnt(3)
	v_pk_add_f32 v[108:109], v[108:109], v[234:235]
	v_pk_add_f32 v[106:107], v[106:107], v[232:233]
	global_load_dwordx4 v[232:235], v[240:241], off offset:112
	s_waitcnt vmcnt(3)
	v_pk_add_f32 v[108:109], v[108:109], v[238:239]
	v_pk_add_f32 v[106:107], v[106:107], v[236:237]
	global_load_dwordx4 v[236:239], v[240:241], off offset:128
	s_waitcnt vmcnt(3)
	v_pk_add_f32 v[108:109], v[108:109], v[226:227]
	v_pk_add_f32 v[106:107], v[106:107], v[224:225]
	global_load_dwordx4 v[224:227], v[240:241], off offset:144
	s_waitcnt vmcnt(3)
	v_pk_add_f32 v[108:109], v[108:109], v[230:231]
	v_pk_add_f32 v[106:107], v[106:107], v[228:229]
	global_load_dwordx4 v[228:231], v[240:241], off offset:160
	s_waitcnt vmcnt(3)
	v_pk_add_f32 v[108:109], v[108:109], v[234:235]
	v_pk_add_f32 v[106:107], v[106:107], v[232:233]
	global_load_dwordx4 v[232:235], v[240:241], off offset:176
	s_waitcnt vmcnt(3)
	v_pk_add_f32 v[108:109], v[108:109], v[238:239]
	v_pk_add_f32 v[106:107], v[106:107], v[236:237]
	global_load_dwordx4 v[236:239], v[240:241], off offset:192
	s_waitcnt vmcnt(3)
	v_pk_add_f32 v[108:109], v[108:109], v[226:227]
	v_pk_add_f32 v[106:107], v[106:107], v[224:225]
	global_load_dwordx4 v[224:227], v[240:241], off offset:208
	s_waitcnt vmcnt(3)
	v_pk_add_f32 v[108:109], v[108:109], v[230:231]
	v_pk_add_f32 v[106:107], v[106:107], v[228:229]
	global_load_dwordx4 v[228:231], v[240:241], off offset:224
	s_waitcnt vmcnt(3)
	v_pk_add_f32 v[108:109], v[108:109], v[234:235]
	v_pk_add_f32 v[106:107], v[106:107], v[232:233]
	global_load_dwordx4 v[232:235], v[240:241], off offset:240
	s_waitcnt vmcnt(3)
	v_pk_add_f32 v[108:109], v[108:109], v[238:239]
	v_pk_add_f32 v[106:107], v[106:107], v[236:237]
	s_waitcnt vmcnt(2)
	v_pk_add_f32 v[108:109], v[108:109], v[226:227]
	v_pk_add_f32 v[106:107], v[106:107], v[224:225]
	s_waitcnt vmcnt(1)
	v_pk_add_f32 v[108:109], v[108:109], v[230:231]
	v_pk_add_f32 v[106:107], v[106:107], v[228:229]
	s_waitcnt vmcnt(0)
	v_pk_add_f32 v[108:109], v[108:109], v[234:235]
	v_pk_add_f32 v[106:107], v[106:107], v[232:233]
	s_branch .Lepc_done
.Lepc_np8:
	s_waitcnt vmcnt(3)
	v_pk_add_f32 v[108:109], v[108:109], v[226:227]
	v_pk_add_f32 v[106:107], v[106:107], v[224:225]
	global_load_dwordx4 v[224:227], v[240:241], off offset:80
	s_waitcnt vmcnt(3)
	v_pk_add_f32 v[108:109], v[108:109], v[230:231]
	v_pk_add_f32 v[106:107], v[106:107], v[228:229]
	global_load_dwordx4 v[228:231], v[240:241], off offset:96
	s_waitcnt vmcnt(3)
	v_pk_add_f32 v[108:109], v[108:109], v[234:235]
	v_pk_add_f32 v[106:107], v[106:107], v[232:233]
	global_load_dwordx4 v[232:235], v[240:241], off offset:112
	s_waitcnt vmcnt(3)
	v_pk_add_f32 v[108:109], v[108:109], v[238:239]
	v_pk_add_f32 v[106:107], v[106:107], v[236:237]
	s_waitcnt vmcnt(2)
	v_pk_add_f32 v[108:109], v[108:109], v[226:227]
	v_pk_add_f32 v[106:107], v[106:107], v[224:225]
	s_waitcnt vmcnt(1)
	v_pk_add_f32 v[108:109], v[108:109], v[230:231]
	v_pk_add_f32 v[106:107], v[106:107], v[228:229]
	s_waitcnt vmcnt(0)
	v_pk_add_f32 v[108:109], v[108:109], v[234:235]
	v_pk_add_f32 v[106:107], v[106:107], v[232:233]
.Lepc_done:
	v_mov_b32_e32 v126, v107
	v_mov_b32_e32 v127, v108
	v_mov_b32_e32 v107, v109
	v_pk_add_f32 v[106:107], v[126:127], v[106:107]
	s_nop 0
	v_add_f32_e32 v106, v106, v107
	v_fmamk_f32 v106, v106, 0x3a000000, v243
	v_rsq_f32_e32 v106, v106
	ds_write_b32 v244, v106
